# sparse attention prologue: rope rows fetched four whole 256-byte rows per load (8 cache lines instead of 32 per load) and re-dealt to the lanes through the wave's LDS stash; the triple-load test had s
# speedup vs baseline: 1.0009x; 1.0009x over previous
.Lnsa_task:
	s_lshr_b32 s65, s26, 8
	s_and_b32 s1, s26, 255
	s_and_b32 s2, s1, 7
	s_lshr_b32 s1, s1, 3
	s_lshl_b32 s2, s2, 5
	s_or_b32 s1, s1, s2
	s_and_b32 s28, s1, 31
	s_sub_i32 s2, 31, s28
	s_bitcmp1_b32 s65, 0
	s_cselect_b32 s28, s2, s28
	s_lshr_b32 s29, s1, 5
	s_lshl_b32 s2, s65, 3
	s_add_i32 s29, s29, s2
	s_lshr_b32 s30, s29, 1
	s_and_b32 s31, s29, 1
	s_lshl_b32 s36, s31, 2
	s_add_i32 s36, s36, s34
	s_lshl_b32 s33, s28, 6
	s_mov_b32 s32, s28
	s_lshl_b32 s2, s35, 5
	s_add_i32 s2, s2, s33
	v_add_u32_e32 v86, s2, v112
	v_add_u32_e32 v87, 16, v86
	s_lshl_b32 s6, s29, 11
	s_add_i32 s7, s6, s33
	v_add_u32_e32 v221, s7, v152
	v_lshlrev_b32_e32 v221, 2, v221
	s_add_u32 s4, s96, 0x2e00000
	s_addc_u32 s5, s97, 0
	global_load_dword v243, v221, s[4:5]
	s_lshl_b32 s3, s30, 11
	v_add_u32_e32 v220, s3, v86
	v_lshlrev_b32_e32 v234, 10, v220
	s_lshl_b32 s4, s36, 7
	v_add_u32_e32 v234, s4, v234
	v_lshl_add_u32 v234, v113, 4, v234
	v_mov_b32_e32 v235, 0
	s_add_u32 s4, s96, 0xe000000
	s_addc_u32 s5, s97, 0
	v_lshl_add_u64 v[234:235], s[4:5], 0, v[234:235]
	global_load_dwordx4 v[160:163], v[234:235], off
	global_load_dwordx4 v[164:167], v[234:235], off offset:64
	s_lshl_b32 s4, s35, 5
	s_add_i32 s4, s4, s33
	s_add_i32 s4, s4, 0
	v_add_u32_e32 v236, s4, v113
	v_lshlrev_b32_e32 v236, 8, v236
	v_lshl_add_u32 v236, v112, 4, v236
	s_add_u32 s4, s96, 0x2c00000
	s_addc_u32 s5, s97, 0
	global_load_dwordx4 v[124:127], v236, s[4:5] offset:0
	global_load_dwordx4 v[128:131], v236, s[4:5] offset:1024
	global_load_dwordx4 v[132:135], v236, s[4:5] offset:2048
	global_load_dwordx4 v[136:139], v236, s[4:5] offset:3072
	s_lshl_b32 s6, s29, 11
	v_add_u32_e32 v221, s6, v86
	v_lshlrev_b32_e32 v221, 2, v221
	s_add_u32 s4, s96, 0x2e00000
	s_addc_u32 s5, s97, 0
	global_load_dword v84, v221, s[4:5]
	v_add_u32_e32 v220, s3, v87
	v_lshlrev_b32_e32 v234, 10, v220
	s_lshl_b32 s4, s36, 7
	v_add_u32_e32 v234, s4, v234
	v_lshl_add_u32 v234, v113, 4, v234
	v_mov_b32_e32 v235, 0
	s_add_u32 s4, s96, 0xe000000
	s_addc_u32 s5, s97, 0
	v_lshl_add_u64 v[234:235], s[4:5], 0, v[234:235]
	global_load_dwordx4 v[168:171], v[234:235], off
	global_load_dwordx4 v[172:175], v[234:235], off offset:64
	s_lshl_b32 s4, s35, 5
	s_add_i32 s4, s4, s33
	s_add_i32 s4, s4, 16
	v_add_u32_e32 v236, s4, v113
	v_lshlrev_b32_e32 v236, 8, v236
	v_lshl_add_u32 v236, v112, 4, v236
	s_add_u32 s4, s96, 0x2c00000
	s_addc_u32 s5, s97, 0
	global_load_dwordx4 v[140:143], v236, s[4:5] offset:0
	global_load_dwordx4 v[144:147], v236, s[4:5] offset:1024
	global_load_dwordx4 v[148:151], v236, s[4:5] offset:2048
	global_load_dwordx4 v[154:157], v236, s[4:5] offset:3072
	s_lshl_b32 s6, s29, 11
	v_add_u32_e32 v221, s6, v87
	v_lshlrev_b32_e32 v221, 2, v221
	s_add_u32 s4, s96, 0x2e00000
	s_addc_u32 s5, s97, 0
	global_load_dword v85, v221, s[4:5]
	s_lshl_b32 s3, s30, 11
	s_mul_i32 s2, s36, 6
	s_add_i32 s2, s2, 2
	s_add_u32 s8, s96, 0x13000000
	s_addc_u32 s9, s97, 0
	v_add_u32_e32 v223, s3, v86
	v_lshlrev_b32_e32 v223, 6, v223
	v_add_u32_e32 v223, s2, v223
	global_load_ushort v119, v223, s[8:9]
	global_load_ushort v158, v223, s[8:9] offset:2
	v_add_u32_e32 v223, s3, v87
	v_lshlrev_b32_e32 v223, 6, v223
	v_add_u32_e32 v223, s2, v223
	global_load_ushort v159, v223, s[8:9]
	global_load_ushort v233, v223, s[8:9] offset:2
	s_add_u32 s8, s96, 0x9000000
	s_addc_u32 s9, s97, 0
	v_add_u32_e32 v223, s3, v86
	v_lshlrev_b32_e32 v223, 10, v223
	s_lshl_b32 s2, s36, 7
	v_add_u32_e32 v223, s2, v223
	v_lshl_add_u32 v223, v113, 3, v223
	global_load_dwordx2 v[16:17], v223, s[8:9] offset:0
	global_load_dwordx2 v[20:21], v223, s[8:9] offset:32
	global_load_dwordx2 v[24:25], v223, s[8:9] offset:64
	global_load_dwordx2 v[28:29], v223, s[8:9] offset:96
	v_add_u32_e32 v223, s3, v87
	v_lshlrev_b32_e32 v223, 10, v223
	s_lshl_b32 s2, s36, 7
	v_add_u32_e32 v223, s2, v223
	v_lshl_add_u32 v223, v113, 3, v223
	global_load_dwordx2 v[32:33], v223, s[8:9] offset:0
	global_load_dwordx2 v[36:37], v223, s[8:9] offset:32
	global_load_dwordx2 v[40:41], v223, s[8:9] offset:64
	global_load_dwordx2 v[44:45], v223, s[8:9] offset:96
	s_mul_i32 s2, s30, 0x300000
	s_add_u32 s8, s96, 0x10000000
	s_addc_u32 s9, s97, 0
	s_add_u32 s8, s8, s2
	s_addc_u32 s9, s9, 0
	s_lshl_b32 s2, s31, 7
	s_add_u32 s8, s8, s2
	s_addc_u32 s9, s9, 0
	s_add_u32 s10, s8, 0x200
	s_addc_u32 s11, s9, 0
	global_load_dwordx4 v[88:91], v117, s[10:11]
	s_lshl_b32 s2, s29, 18
	s_add_u32 s10, s96, 0x1b200000
	s_addc_u32 s11, s97, 0
	s_add_u32 s10, s10, s2
	s_addc_u32 s11, s11, 0
	global_load_dwordx4 v[92:95], v118, s[10:11]
	s_add_i32 s12, s32, -8
	s_max_i32 s12, s12, 0
	s_mul_i32 s13, s12, 0x18000
	s_add_u32 s10, s8, 0x400
	s_addc_u32 s11, s9, 0
	s_add_u32 s10, s10, s13
	s_addc_u32 s11, s11, 0
	global_load_dwordx4 v[192:195], v117, s[10:11]
	s_lshl_b32 s13, s12, 7
	s_add_u32 s10, s96, 0x1ba00000
	s_addc_u32 s11, s97, 0
	s_add_u32 s10, s10, s2
	s_addc_u32 s11, s11, 0
	s_add_u32 s10, s10, s13
	s_addc_u32 s11, s11, 0
	global_load_dwordx4 v[196:199], v118, s[10:11]
	s_waitcnt vmcnt(30)
	s_nop 0
	v_or_b32_dpp v243, v243, v243 quad_perm:[1,0,3,2] row_mask:0xf bank_mask:0xf bound_ctrl:1
	s_nop 1
	v_or_b32_dpp v243, v243, v243 quad_perm:[2,3,0,1] row_mask:0xf bank_mask:0xf bound_ctrl:1
	s_nop 1
	v_or_b32_dpp v243, v243, v243 row_ror:4 row_mask:0xf bank_mask:0xf bound_ctrl:1
	s_nop 1
	v_or_b32_dpp v243, v243, v243 row_ror:8 row_mask:0xf bank_mask:0xf bound_ctrl:1
	v_mov_b32_e32 v242, v243
	s_nop 1
	v_permlane16_swap_b32_e32 v243, v242
	v_or_b32_e32 v243, v243, v242
	v_mov_b32_e32 v242, v243
	s_nop 1
	v_permlane32_swap_b32_e32 v243, v242
	v_or_b32_e32 v243, v243, v242
	s_nop 0
	v_readfirstlane_b32 s39, v243
	s_add_u32 s46, s8, 0x200
	s_addc_u32 s47, s9, 0
	s_lshl_b32 s2, s29, 18
	s_add_u32 s48, s96, 0x1b200000
	s_addc_u32 s49, s97, 0
	s_add_u32 s48, s48, s2
	s_addc_u32 s49, s49, 0
	s_lshl_b32 s2, 2, s32
	s_add_i32 s2, s2, -1
	s_and_b32 s38, s39, s2
	s_ff1_i32_b32 s15, s38
	s_add_i32 s65, s38, -1
	s_and_b32 s38, s38, s65
	s_ff1_i32_b32 s41, s38
	s_add_i32 s65, s38, -1
	s_and_b32 s38, s38, s65
	s_ff1_i32_b32 s42, s38
	s_add_i32 s65, s38, -1
	s_and_b32 s38, s38, s65
	s_cmp_eq_u32 s15, 0
	s_cbranch_scc1 .Lnsa_e0_1
	s_mov_b32 s40, s15
	s_max_i32 s65, s40, 0
	s_mul_i32 s56, s65, 0x18000
	s_lshl_b32 s58, s65, 7
	s_add_u32 s56, s46, s56
	s_addc_u32 s57, s47, 0
	s_add_u32 s58, s48, s58
	s_addc_u32 s59, s49, 0
	global_load_dwordx4 v[88:91], v117, s[56:57]
	global_load_dwordx4 v[92:95], v118, s[58:59]
.Lnsa_e0_1:
	s_max_i32 s65, s41, 0
	s_mul_i32 s56, s65, 0x18000
	s_lshl_b32 s58, s65, 7
	s_add_u32 s56, s46, s56
	s_addc_u32 s57, s47, 0
	s_add_u32 s58, s48, s58
	s_addc_u32 s59, s49, 0
	global_load_dwordx4 v[96:99], v117, s[56:57]
	global_load_dwordx4 v[100:103], v118, s[58:59]
	s_max_i32 s65, s42, 0
	s_mul_i32 s56, s65, 0x18000
	s_lshl_b32 s58, s65, 7
	s_add_u32 s56, s46, s56
	s_addc_u32 s57, s47, 0
	s_add_u32 s58, s48, s58
	s_addc_u32 s59, s49, 0
	global_load_dwordx4 v[104:107], v117, s[56:57]
	global_load_dwordx4 v[108:111], v118, s[58:59]
	s_waitcnt vmcnt(4)
	v_lshlrev_b32_e32 v220, 4, v152
	v_sub_u32_e32 v220, v250, v220
	v_xor_b32_e32 v240, v112, v113
	v_lshlrev_b32_e32 v240, 4, v240
	v_lshl_add_u32 v240, v113, 8, v240
	v_add_u32_e32 v240, v220, v240
	v_xor_b32_e32 v241, 0xc0, v240
	ds_write_b128 v240, v[124:127] offset:0
	ds_write_b128 v240, v[128:131] offset:1024
	ds_write_b128 v241, v[132:135] offset:2048
	ds_write_b128 v241, v[136:139] offset:3072
	ds_write_b128 v240, v[140:143] offset:4096
	ds_write_b128 v240, v[144:147] offset:5120
	ds_write_b128 v241, v[148:151] offset:6144
	ds_write_b128 v241, v[154:157] offset:7168
	v_add_u32_e32 v242, -4, v112
	v_cmp_gt_u32_e32 vcc, 8, v242
	v_xor_b32_e32 v243, 4, v112
	s_nop 0
	v_cndmask_b32_e32 v243, v112, v243, vcc
	v_lshlrev_b32_e32 v242, 2, v113
	v_add_u32_e32 v244, 0, v242
	v_xor_b32_e32 v244, v244, v243
	v_lshlrev_b32_e32 v244, 4, v244
	v_lshl_add_u32 v244, v112, 8, v244
	v_add_u32_e32 v244, v220, v244
	v_add_u32_e32 v245, 1, v242
	v_xor_b32_e32 v245, v245, v243
	v_lshlrev_b32_e32 v245, 4, v245
	v_lshl_add_u32 v245, v112, 8, v245
	v_add_u32_e32 v245, v220, v245
	v_add_u32_e32 v246, 2, v242
	v_xor_b32_e32 v246, v246, v243
	v_lshlrev_b32_e32 v246, 4, v246
	v_lshl_add_u32 v246, v112, 8, v246
	v_add_u32_e32 v246, v220, v246
	v_add_u32_e32 v247, 3, v242
	v_xor_b32_e32 v247, v247, v243
	v_lshlrev_b32_e32 v247, 4, v247
	v_lshl_add_u32 v247, v112, 8, v247
	v_add_u32_e32 v247, v220, v247
	s_waitcnt lgkmcnt(0)
	ds_read_b128 v[124:127], v244 offset:0
	ds_read_b128 v[128:131], v245 offset:0
	ds_read_b128 v[132:135], v246 offset:0
	ds_read_b128 v[136:139], v247 offset:0
	ds_read_b128 v[140:143], v244 offset:4096
	ds_read_b128 v[144:147], v245 offset:4096
	ds_read_b128 v[148:151], v246 offset:4096
	ds_read_b128 v[154:157], v247 offset:4096
	s_waitcnt lgkmcnt(0)
	s_mov_b32 s7, 0x3e38aa3b
	v_lshlrev_b32_e32 v220, 16, v160
	v_lshlrev_b32_e32 v221, 16, v164
	v_mul_f32_e32 v222, v221, v125
	v_fma_f32 v222, v220, v124, -v222
	v_mul_f32_e32 v223, v220, v125
	v_fma_f32 v223, v221, v124, v223
	v_mul_f32_e32 v240, s7, v222
	v_mul_f32_e32 v244, s7, v223
	v_and_b32_e32 v220, 0xffff0000, v160
	v_and_b32_e32 v221, 0xffff0000, v164
	v_mul_f32_e32 v222, v221, v127
	v_fma_f32 v222, v220, v126, -v222
	v_mul_f32_e32 v223, v220, v127
	v_fma_f32 v223, v221, v126, v223
	v_mul_f32_e32 v241, s7, v222
	v_mul_f32_e32 v245, s7, v223
	v_lshlrev_b32_e32 v220, 16, v161
	v_lshlrev_b32_e32 v221, 16, v165
	v_mul_f32_e32 v222, v221, v129
	v_fma_f32 v222, v220, v128, -v222
	v_mul_f32_e32 v223, v220, v129
	v_fma_f32 v223, v221, v128, v223
	v_mul_f32_e32 v242, s7, v222
	v_mul_f32_e32 v246, s7, v223
	v_and_b32_e32 v220, 0xffff0000, v161
	v_and_b32_e32 v221, 0xffff0000, v165
	v_mul_f32_e32 v222, v221, v131
	v_fma_f32 v222, v220, v130, -v222
	v_mul_f32_e32 v223, v220, v131
	v_fma_f32 v223, v221, v130, v223
	v_mul_f32_e32 v243, s7, v222
	v_mul_f32_e32 v247, s7, v223
	v_cvt_pk_bf16_f32 v0, v240, v241
	v_cvt_pk_bf16_f32 v1, v242, v243
	v_cvt_pk_bf16_f32 v4, v244, v245
	v_cvt_pk_bf16_f32 v5, v246, v247
	v_lshlrev_b32_e32 v220, 16, v162
	v_lshlrev_b32_e32 v221, 16, v166
	v_mul_f32_e32 v222, v221, v133
	v_fma_f32 v222, v220, v132, -v222
	v_mul_f32_e32 v223, v220, v133
	v_fma_f32 v223, v221, v132, v223
	v_mul_f32_e32 v240, s7, v222
	v_mul_f32_e32 v244, s7, v223
	v_and_b32_e32 v220, 0xffff0000, v162
	v_and_b32_e32 v221, 0xffff0000, v166
	v_mul_f32_e32 v222, v221, v135
	v_fma_f32 v222, v220, v134, -v222
	v_mul_f32_e32 v223, v220, v135
	v_fma_f32 v223, v221, v134, v223
	v_mul_f32_e32 v241, s7, v222
	v_mul_f32_e32 v245, s7, v223
	v_lshlrev_b32_e32 v220, 16, v163
	v_lshlrev_b32_e32 v221, 16, v167
	v_mul_f32_e32 v222, v221, v137
	v_fma_f32 v222, v220, v136, -v222
	v_mul_f32_e32 v223, v220, v137
	v_fma_f32 v223, v221, v136, v223
	v_mul_f32_e32 v242, s7, v222
	v_mul_f32_e32 v246, s7, v223
	v_and_b32_e32 v220, 0xffff0000, v163
	v_and_b32_e32 v221, 0xffff0000, v167
	v_mul_f32_e32 v222, v221, v139
	v_fma_f32 v222, v220, v138, -v222
	v_mul_f32_e32 v223, v220, v139
	v_fma_f32 v223, v221, v138, v223
	v_mul_f32_e32 v243, s7, v222
	v_mul_f32_e32 v247, s7, v223
	v_cvt_pk_bf16_f32 v2, v240, v241
	v_cvt_pk_bf16_f32 v3, v242, v243
	v_cvt_pk_bf16_f32 v6, v244, v245
	v_cvt_pk_bf16_f32 v7, v246, v247
	v_lshlrev_b32_e32 v220, 16, v168
	v_lshlrev_b32_e32 v221, 16, v172
	v_mul_f32_e32 v222, v221, v141
	v_fma_f32 v222, v220, v140, -v222
	v_mul_f32_e32 v223, v220, v141
	v_fma_f32 v223, v221, v140, v223
	v_mul_f32_e32 v240, s7, v222
	v_mul_f32_e32 v244, s7, v223
	v_and_b32_e32 v220, 0xffff0000, v168
	v_and_b32_e32 v221, 0xffff0000, v172
	v_mul_f32_e32 v222, v221, v143
	v_fma_f32 v222, v220, v142, -v222
	v_mul_f32_e32 v223, v220, v143
	v_fma_f32 v223, v221, v142, v223
	v_mul_f32_e32 v241, s7, v222
	v_mul_f32_e32 v245, s7, v223
	v_lshlrev_b32_e32 v220, 16, v169
	v_lshlrev_b32_e32 v221, 16, v173
	v_mul_f32_e32 v222, v221, v145
	v_fma_f32 v222, v220, v144, -v222
	v_mul_f32_e32 v223, v220, v145
	v_fma_f32 v223, v221, v144, v223
	v_mul_f32_e32 v242, s7, v222
	v_mul_f32_e32 v246, s7, v223
	v_and_b32_e32 v220, 0xffff0000, v169
	v_and_b32_e32 v221, 0xffff0000, v173
	v_mul_f32_e32 v222, v221, v147
	v_fma_f32 v222, v220, v146, -v222
	v_mul_f32_e32 v223, v220, v147
	v_fma_f32 v223, v221, v146, v223
	v_mul_f32_e32 v243, s7, v222
	v_mul_f32_e32 v247, s7, v223
	v_cvt_pk_bf16_f32 v8, v240, v241
	v_cvt_pk_bf16_f32 v9, v242, v243
	v_cvt_pk_bf16_f32 v12, v244, v245
	v_cvt_pk_bf16_f32 v13, v246, v247
	v_lshlrev_b32_e32 v220, 16, v170
	v_lshlrev_b32_e32 v221, 16, v174
	v_mul_f32_e32 v222, v221, v149
	v_fma_f32 v222, v220, v148, -v222
	v_mul_f32_e32 v223, v220, v149
	v_fma_f32 v223, v221, v148, v223
	v_mul_f32_e32 v240, s7, v222
	v_mul_f32_e32 v244, s7, v223
	v_and_b32_e32 v220, 0xffff0000, v170
	v_and_b32_e32 v221, 0xffff0000, v174
	v_mul_f32_e32 v222, v221, v151
	v_fma_f32 v222, v220, v150, -v222
	v_mul_f32_e32 v223, v220, v151
	v_fma_f32 v223, v221, v150, v223
	v_mul_f32_e32 v241, s7, v222
	v_mul_f32_e32 v245, s7, v223
	v_lshlrev_b32_e32 v220, 16, v171
	v_lshlrev_b32_e32 v221, 16, v175
	v_mul_f32_e32 v222, v221, v155
	v_fma_f32 v222, v220, v154, -v222
	v_mul_f32_e32 v223, v220, v155
	v_fma_f32 v223, v221, v154, v223
	v_mul_f32_e32 v242, s7, v222
	v_mul_f32_e32 v246, s7, v223
	v_and_b32_e32 v220, 0xffff0000, v171
	v_and_b32_e32 v221, 0xffff0000, v175
	v_mul_f32_e32 v222, v221, v157
	v_fma_f32 v222, v220, v156, -v222
	v_mul_f32_e32 v223, v220, v157
	v_fma_f32 v223, v221, v156, v223
	v_mul_f32_e32 v243, s7, v222
	v_mul_f32_e32 v247, s7, v223
	v_cvt_pk_bf16_f32 v10, v240, v241
	v_cvt_pk_bf16_f32 v11, v242, v243
	v_cvt_pk_bf16_f32 v14, v244, v245
	v_cvt_pk_bf16_f32 v15, v246, v247
	v_and_b32_e32 v19, 0xffff0000, v17
	v_lshlrev_b32_e32 v18, 16, v17
	v_and_b32_e32 v17, 0xffff0000, v16
	v_lshlrev_b32_e32 v16, 16, v16
	v_and_b32_e32 v23, 0xffff0000, v21
	v_lshlrev_b32_e32 v22, 16, v21
	v_and_b32_e32 v21, 0xffff0000, v20
	v_lshlrev_b32_e32 v20, 16, v20
	v_and_b32_e32 v27, 0xffff0000, v25
	v_lshlrev_b32_e32 v26, 16, v25
	v_and_b32_e32 v25, 0xffff0000, v24
	v_lshlrev_b32_e32 v24, 16, v24
	v_and_b32_e32 v31, 0xffff0000, v29
	v_lshlrev_b32_e32 v30, 16, v29
	v_and_b32_e32 v29, 0xffff0000, v28
	v_lshlrev_b32_e32 v28, 16, v28
	v_and_b32_e32 v35, 0xffff0000, v33
	v_lshlrev_b32_e32 v34, 16, v33
	v_and_b32_e32 v33, 0xffff0000, v32
	v_lshlrev_b32_e32 v32, 16, v32
	v_and_b32_e32 v39, 0xffff0000, v37
	v_lshlrev_b32_e32 v38, 16, v37
	v_and_b32_e32 v37, 0xffff0000, v36
	v_lshlrev_b32_e32 v36, 16, v36
	v_and_b32_e32 v43, 0xffff0000, v41
	v_lshlrev_b32_e32 v42, 16, v41
	v_and_b32_e32 v41, 0xffff0000, v40
	v_lshlrev_b32_e32 v40, 16, v40
	v_and_b32_e32 v47, 0xffff0000, v45
	v_lshlrev_b32_e32 v46, 16, v45
	v_and_b32_e32 v45, 0xffff0000, v44
	v_lshlrev_b32_e32 v44, 16, v44
	ds_write_b128 v250, v[16:19] offset:0
	ds_write_b128 v250, v[20:23] offset:1024
	ds_write_b128 v250, v[24:27] offset:2048
	ds_write_b128 v250, v[28:31] offset:3072
	ds_write_b128 v250, v[32:35] offset:4096
	ds_write_b128 v250, v[36:39] offset:5120
	ds_write_b128 v250, v[40:43] offset:6144
	ds_write_b128 v250, v[44:47] offset:7168
	s_waitcnt lgkmcnt(0)
	s_mov_b32 s37, 0
